# v41: P5 only - accumulator zeroing for the next unit interleaved into the SwiGLU epilogue
# speedup vs baseline: 1.0024x; 1.0002x over previous
.LBB0_1552:
	s_add_u32 s6, s46, 0x7100000
	s_addc_u32 s7, s47, 0
	s_add_u32 s8, s46, 0x1b00000
	s_addc_u32 s9, s47, 0
	s_lshl_b32 s10, s10, 5
	s_and_b32 s16, s10, 0x60
	s_mov_b64 s[10:11], 0x80
	s_add_i32 m0, s23, 0x18000
	v_lshl_add_u64 v[8:9], v[8:9], 0, s[10:11]
	s_lshl_b32 s13, s12, 13
	s_lshl_b32 s17, s16, 7
	s_waitcnt vmcnt(2)
	s_barrier
	global_load_lds_dwordx4 v[8:9], off
	v_lshl_add_u64 v[6:7], v[6:7], 0, s[10:11]
	s_add_i32 m0, s23, 0x1a000
	s_add_i32 s42, s23, 0x8000
	s_add_i32 s43, s23, 0xa000
	global_load_lds_dwordx4 v[6:7], off
	v_lshl_add_u64 v[2:3], v[2:3], 0, s[10:11]
	s_mov_b32 m0, s42
	s_add_u32 s14, s26, 0x40080
	global_load_lds_dwordx4 v[2:3], off
	v_lshl_add_u64 v[2:3], v[4:5], 0, s[10:11]
	s_mov_b32 m0, s43
	s_addc_u32 s15, s27, 0
	global_load_lds_dwordx4 v[2:3], off
	s_add_i32 m0, s23, 0x1c000
	v_lshl_add_u64 v[2:3], s[14:15], 0, v[134:135]
	global_load_lds_dwordx4 v[2:3], off
	v_lshl_add_u64 v[2:3], s[14:15], 0, v[130:131]
	s_add_i32 m0, s23, 0x1e000
	s_sext_i32_i16 s50, s2
	global_load_lds_dwordx4 v[2:3], off
	v_and_b32_e32 v2, 15, v1
	v_lshlrev_b32_e32 v3, 1, v13
	v_lshlrev_b32_e32 v5, 6, v1
	s_movk_i32 s2, 0x3c0
	v_lshl_or_b32 v150, s12, 6, v2
	v_lshl_or_b32 v2, v2, 6, v3
	v_and_b32_e32 v4, 32, v178
	v_and_or_b32 v3, v5, s2, v3
	v_bitop3_b32 v151, s17, v3, v4 bitop3:0xf6
	v_lshlrev_b32_e32 v3, 8, v1
	v_bitop3_b32 v2, v2, s13, v4 bitop3:0xde
	v_and_b32_e32 v3, 0x38000, v3
	v_lshlrev_b32_e32 v4, 11, v14
	v_or3_b32 v3, v11, v3, v4
	v_add_u32_e32 v138, v3, v12
	v_lshlrev_b32_e32 v3, 4, v10
	s_waitcnt vmcnt(6)
	s_cmpk_lt_u32 s3, 0x100
	v_and_b32_e32 v3, 0x78000, v3
	s_cselect_b64 s[12:13], -1, 0
	v_or3_b32 v3, v11, v3, v4
	s_add_i32 s45, 0, 0x10000
	s_add_i32 s48, 0, 0x14000
	s_ashr_i32 s44, s91, 31
	v_or_b32_e32 v152, s16, v13
	v_mov_b32_e32 v139, v135
	v_add_u32_e32 v140, v3, v12
	v_mov_b32_e32 v141, v135
	v_mov_b64_e32 v[142:143], 0x5d8
	v_mov_b64_e32 v[144:145], 0x5d7
	v_add_u32_e32 v153, s45, v151
	v_add_u32_e32 v154, s48, v151
	v_add_u32_e32 v155, 0, v2
	s_movk_i32 s49, 0x1600
	s_mov_b32 s59, 0
	s_barrier
	s_branch .LBB0_1555

.LBB0_1557:
	s_ashr_i32 s17, s16, 31
	s_lshl_b64 s[18:19], s[16:17], 19
	s_add_u32 s18, s33, s18
	s_addc_u32 s19, s34, s19
	s_and_b64 s[20:21], s[2:3], exec
	s_cselect_b32 s17, s19, s25
	s_cselect_b32 s51, s18, s24
	s_ashr_i32 s15, s14, 31
	s_lshl_b64 s[20:21], s[14:15], 19
	s_add_u32 s20, s30, s20
	s_addc_u32 s21, s31, s21
	s_and_b64 s[28:29], s[2:3], exec
	s_cselect_b32 s15, s21, s27
	s_cselect_b32 s52, s20, s26
	s_add_u32 s24, s24, 0x40080
	s_addc_u32 s25, s25, 0
	s_add_u32 s53, s26, 0x100
	v_mov_b32_e32 v2, 0
	s_addc_u32 s54, s27, 0
	s_mov_b32 s55, -2
	s_cmp_eq_u32 s59, 1
	s_cbranch_scc1 .Lp5_nozero
	v_mov_b32_e32 v3, v2
	v_mov_b32_e32 v4, v2
	v_mov_b32_e32 v5, v2
	v_mov_b32_e32 v14, v2
	v_mov_b32_e32 v15, v2
	v_mov_b32_e32 v16, v2
	v_mov_b32_e32 v17, v2
	v_mov_b32_e32 v18, v2
	v_mov_b32_e32 v19, v2
	v_mov_b32_e32 v20, v2
	v_mov_b32_e32 v21, v2
	v_mov_b32_e32 v30, v2
	v_mov_b32_e32 v31, v2
	v_mov_b32_e32 v32, v2
	v_mov_b32_e32 v33, v2
	v_mov_b32_e32 v34, v2
	v_mov_b32_e32 v35, v2
	v_mov_b32_e32 v36, v2
	v_mov_b32_e32 v37, v2
	v_mov_b32_e32 v46, v2
	v_mov_b32_e32 v47, v2
	v_mov_b32_e32 v48, v2
	v_mov_b32_e32 v49, v2
	v_mov_b32_e32 v50, v2
	v_mov_b32_e32 v51, v2
	v_mov_b32_e32 v52, v2
	v_mov_b32_e32 v53, v2
	v_mov_b32_e32 v62, v2
	v_mov_b32_e32 v63, v2
	v_mov_b32_e32 v64, v2
	v_mov_b32_e32 v65, v2
	v_mov_b32_e32 v6, v2
	v_mov_b32_e32 v7, v2
	v_mov_b32_e32 v8, v2
	v_mov_b32_e32 v9, v2
	v_mov_b32_e32 v10, v2
	v_mov_b32_e32 v11, v2
	v_mov_b32_e32 v12, v2
	v_mov_b32_e32 v13, v2
	v_mov_b32_e32 v22, v2
	v_mov_b32_e32 v23, v2
	v_mov_b32_e32 v24, v2
	v_mov_b32_e32 v25, v2
	v_mov_b32_e32 v26, v2
	v_mov_b32_e32 v27, v2
	v_mov_b32_e32 v28, v2
	v_mov_b32_e32 v29, v2
	v_mov_b32_e32 v38, v2
	v_mov_b32_e32 v39, v2
	v_mov_b32_e32 v40, v2
	v_mov_b32_e32 v41, v2
	v_mov_b32_e32 v42, v2
	v_mov_b32_e32 v43, v2
	v_mov_b32_e32 v44, v2
	v_mov_b32_e32 v45, v2
	v_mov_b32_e32 v54, v2
	v_mov_b32_e32 v55, v2
	v_mov_b32_e32 v56, v2
	v_mov_b32_e32 v57, v2
	v_mov_b32_e32 v58, v2
	v_mov_b32_e32 v59, v2
	v_mov_b32_e32 v60, v2
	v_mov_b32_e32 v61, v2
	v_mov_b32_e32 v66, v2
	v_mov_b32_e32 v67, v2
	v_mov_b32_e32 v68, v2
	v_mov_b32_e32 v69, v2
	v_mov_b32_e32 v78, v2
	v_mov_b32_e32 v79, v2
	v_mov_b32_e32 v80, v2
	v_mov_b32_e32 v81, v2
	v_mov_b32_e32 v86, v2
	v_mov_b32_e32 v87, v2
	v_mov_b32_e32 v88, v2
	v_mov_b32_e32 v89, v2
	v_mov_b32_e32 v94, v2
	v_mov_b32_e32 v95, v2
	v_mov_b32_e32 v96, v2
	v_mov_b32_e32 v97, v2
	v_mov_b32_e32 v102, v2
	v_mov_b32_e32 v103, v2
	v_mov_b32_e32 v104, v2
	v_mov_b32_e32 v105, v2
	v_mov_b32_e32 v110, v2
	v_mov_b32_e32 v111, v2
	v_mov_b32_e32 v112, v2
	v_mov_b32_e32 v113, v2
	v_mov_b32_e32 v118, v2
	v_mov_b32_e32 v119, v2
	v_mov_b32_e32 v120, v2
	v_mov_b32_e32 v121, v2
	v_mov_b32_e32 v126, v2
	v_mov_b32_e32 v127, v2
	v_mov_b32_e32 v128, v2
	v_mov_b32_e32 v129, v2
	v_mov_b32_e32 v70, v2
	v_mov_b32_e32 v71, v2
	v_mov_b32_e32 v72, v2
	v_mov_b32_e32 v73, v2
	v_mov_b32_e32 v74, v2
	v_mov_b32_e32 v75, v2
	v_mov_b32_e32 v76, v2
	v_mov_b32_e32 v77, v2
	v_mov_b32_e32 v82, v2
	v_mov_b32_e32 v83, v2
	v_mov_b32_e32 v84, v2
	v_mov_b32_e32 v85, v2
	v_mov_b32_e32 v90, v2
	v_mov_b32_e32 v91, v2
	v_mov_b32_e32 v92, v2
	v_mov_b32_e32 v93, v2
	v_mov_b32_e32 v98, v2
	v_mov_b32_e32 v99, v2
	v_mov_b32_e32 v100, v2
	v_mov_b32_e32 v101, v2
	v_mov_b32_e32 v106, v2
	v_mov_b32_e32 v107, v2
	v_mov_b32_e32 v108, v2
	v_mov_b32_e32 v109, v2
	v_mov_b32_e32 v114, v2
	v_mov_b32_e32 v115, v2
	v_mov_b32_e32 v116, v2
	v_mov_b32_e32 v117, v2
	v_mov_b32_e32 v122, v2
	v_mov_b32_e32 v123, v2
	v_mov_b32_e32 v124, v2
	v_mov_b32_e32 v125, v2
.Lp5_nozero:
.LBB0_1558:
	ds_read_b128 v[146:149], v153
	ds_read_b128 v[156:159], v153 offset:1024
	ds_read_b128 v[160:163], v153 offset:2048
	ds_read_b128 v[164:167], v153 offset:3072
	ds_read_b128 v[168:171], v154
	ds_read_b128 v[172:175], v154 offset:1024
	ds_read_b128 v[180:183], v154 offset:2048
	ds_read_b128 v[184:187], v154 offset:3072
	s_add_u32 s26, s24, 0xfffc0080
	s_addc_u32 s27, s25, -1
	s_cmp_eq_u32 s55, 12
	s_cselect_b32 s29, s17, s27
	s_cselect_b32 s28, s51, s26
	s_cselect_b32 s27, s15, s54
	s_cselect_b32 s26, s52, s53
	v_lshl_add_u64 v[176:177], s[24:25], 0, v[138:139]
	s_add_i32 m0, s23, 0xc000
	ds_read_b128 v[188:191], v155
	ds_read_b128 v[192:195], v155 offset:1024
	ds_read_b128 v[196:199], v155 offset:2048
	ds_read_b128 v[200:203], v155 offset:3072
	ds_read_b128 v[204:207], v155 offset:4096
	ds_read_b128 v[210:213], v155 offset:5120
	ds_read_b128 v[214:217], v155 offset:6144
	ds_read_b128 v[218:221], v155 offset:7168
	global_load_lds_dwordx4 v[176:177], off
	v_lshl_add_u64 v[176:177], s[24:25], 0, v[140:141]
	s_add_i32 m0, s23, 0xe000
	s_nop 0
	global_load_lds_dwordx4 v[176:177], off
	s_waitcnt vmcnt(8)
	s_waitcnt lgkmcnt(0)
	s_barrier
	s_setprio 1
	s_waitcnt lgkmcnt(0)
	v_mfma_f32_16x16x32_bf16 v[122:125], v[146:149], v[188:191], v[122:125]
	v_mfma_f32_16x16x32_bf16 v[114:117], v[160:163], v[188:191], v[114:117]
	v_mfma_f32_16x16x32_bf16 v[106:109], v[146:149], v[196:199], v[106:109]
	v_mfma_f32_16x16x32_bf16 v[98:101], v[160:163], v[196:199], v[98:101]
	v_mfma_f32_16x16x32_bf16 v[90:93], v[146:149], v[204:207], v[90:93]
	v_mfma_f32_16x16x32_bf16 v[82:85], v[160:163], v[204:207], v[82:85]
	v_mfma_f32_16x16x32_bf16 v[74:77], v[146:149], v[214:217], v[74:77]
	v_mfma_f32_16x16x32_bf16 v[70:73], v[160:163], v[214:217], v[70:73]
	v_mfma_f32_16x16x32_bf16 v[122:125], v[156:159], v[192:195], v[122:125]
	v_mfma_f32_16x16x32_bf16 v[114:117], v[164:167], v[192:195], v[114:117]
	v_mfma_f32_16x16x32_bf16 v[106:109], v[156:159], v[200:203], v[106:109]
	v_mfma_f32_16x16x32_bf16 v[98:101], v[164:167], v[200:203], v[98:101]
	v_mfma_f32_16x16x32_bf16 v[90:93], v[156:159], v[210:213], v[90:93]
	v_mfma_f32_16x16x32_bf16 v[82:85], v[164:167], v[210:213], v[82:85]
	v_mfma_f32_16x16x32_bf16 v[74:77], v[156:159], v[218:221], v[74:77]
	v_mfma_f32_16x16x32_bf16 v[70:73], v[164:167], v[218:221], v[70:73]
	s_setprio 0
	s_setprio 1
	v_mfma_f32_16x16x32_bf16 v[126:129], v[168:171], v[188:191], v[126:129]
	v_mfma_f32_16x16x32_bf16 v[118:121], v[180:183], v[188:191], v[118:121]
	v_mfma_f32_16x16x32_bf16 v[110:113], v[168:171], v[196:199], v[110:113]
	v_mfma_f32_16x16x32_bf16 v[102:105], v[180:183], v[196:199], v[102:105]
	v_mfma_f32_16x16x32_bf16 v[94:97], v[168:171], v[204:207], v[94:97]
	v_mfma_f32_16x16x32_bf16 v[86:89], v[180:183], v[204:207], v[86:89]
	v_mfma_f32_16x16x32_bf16 v[78:81], v[168:171], v[214:217], v[78:81]
	v_mfma_f32_16x16x32_bf16 v[66:69], v[180:183], v[214:217], v[66:69]
	v_mfma_f32_16x16x32_bf16 v[126:129], v[172:175], v[192:195], v[126:129]
	v_mfma_f32_16x16x32_bf16 v[118:121], v[184:187], v[192:195], v[118:121]
	v_mfma_f32_16x16x32_bf16 v[110:113], v[172:175], v[200:203], v[110:113]
	v_mfma_f32_16x16x32_bf16 v[102:105], v[184:187], v[200:203], v[102:105]
	v_mfma_f32_16x16x32_bf16 v[94:97], v[172:175], v[210:213], v[94:97]
	v_mfma_f32_16x16x32_bf16 v[86:89], v[184:187], v[210:213], v[86:89]
	v_mfma_f32_16x16x32_bf16 v[78:81], v[172:175], v[218:221], v[78:81]
	v_mfma_f32_16x16x32_bf16 v[66:69], v[184:187], v[218:221], v[66:69]
	s_setprio 0
	s_barrier
	s_add_i32 s56, s45, s35
	v_lshl_add_u64 v[176:177], s[26:27], 0, v[134:135]
	s_mov_b32 m0, s56
	ds_read_b128 v[188:191], v155 offset:16384
	ds_read_b128 v[192:195], v155 offset:17408
	ds_read_b128 v[196:199], v155 offset:18432
	ds_read_b128 v[200:203], v155 offset:19456
	ds_read_b128 v[204:207], v155 offset:20480
	ds_read_b128 v[210:213], v155 offset:21504
	ds_read_b128 v[214:217], v155 offset:22528
	ds_read_b128 v[218:221], v155 offset:23552
	global_load_lds_dwordx4 v[176:177], off
	s_add_i32 m0, s56, 0x2000
	s_add_u32 s56, s26, 0x40000
	v_lshl_add_u64 v[208:209], s[26:27], 0, v[130:131]
	s_addc_u32 s57, s27, 0
	s_add_i32 s58, s48, s35
	global_load_lds_dwordx4 v[208:209], off
	v_lshl_add_u64 v[222:223], s[56:57], 0, v[134:135]
	s_mov_b32 m0, s58
	v_lshl_add_u64 v[224:225], s[28:29], 0, v[132:133]
	global_load_lds_dwordx4 v[222:223], off
	v_lshl_add_u64 v[222:223], s[56:57], 0, v[130:131]
	s_add_i32 m0, s58, 0x2000
	s_nop 0
	global_load_lds_dwordx4 v[222:223], off
	v_lshl_add_u64 v[222:223], s[28:29], 0, v[136:137]
	s_mov_b32 m0, s23
	s_nop 0
	global_load_lds_dwordx4 v[222:223], off
	s_mov_b32 m0, s38
	s_nop 0
	global_load_lds_dwordx4 v[224:225], off
	s_waitcnt vmcnt(8)
	s_waitcnt lgkmcnt(0)
	s_barrier
	s_setprio 1
	s_waitcnt lgkmcnt(0)
	v_mfma_f32_16x16x32_bf16 v[58:61], v[146:149], v[188:191], v[58:61]
	v_mfma_f32_16x16x32_bf16 v[54:57], v[160:163], v[188:191], v[54:57]
	v_mfma_f32_16x16x32_bf16 v[42:45], v[146:149], v[196:199], v[42:45]
	v_mfma_f32_16x16x32_bf16 v[38:41], v[160:163], v[196:199], v[38:41]
	v_mfma_f32_16x16x32_bf16 v[26:29], v[146:149], v[204:207], v[26:29]
	v_mfma_f32_16x16x32_bf16 v[22:25], v[160:163], v[204:207], v[22:25]
	v_mfma_f32_16x16x32_bf16 v[10:13], v[146:149], v[214:217], v[10:13]
	v_mfma_f32_16x16x32_bf16 v[6:9], v[160:163], v[214:217], v[6:9]
	v_mfma_f32_16x16x32_bf16 v[58:61], v[156:159], v[192:195], v[58:61]
	v_mfma_f32_16x16x32_bf16 v[54:57], v[164:167], v[192:195], v[54:57]
	v_mfma_f32_16x16x32_bf16 v[42:45], v[156:159], v[200:203], v[42:45]
	v_mfma_f32_16x16x32_bf16 v[38:41], v[164:167], v[200:203], v[38:41]
	v_mfma_f32_16x16x32_bf16 v[26:29], v[156:159], v[210:213], v[26:29]
	v_mfma_f32_16x16x32_bf16 v[22:25], v[164:167], v[210:213], v[22:25]
	v_mfma_f32_16x16x32_bf16 v[10:13], v[156:159], v[218:221], v[10:13]
	v_mfma_f32_16x16x32_bf16 v[6:9], v[164:167], v[218:221], v[6:9]
	s_setprio 0
	s_setprio 1
	v_mfma_f32_16x16x32_bf16 v[62:65], v[168:171], v[188:191], v[62:65]
	v_mfma_f32_16x16x32_bf16 v[50:53], v[180:183], v[188:191], v[50:53]
	v_mfma_f32_16x16x32_bf16 v[46:49], v[168:171], v[196:199], v[46:49]
	v_mfma_f32_16x16x32_bf16 v[34:37], v[180:183], v[196:199], v[34:37]
	v_mfma_f32_16x16x32_bf16 v[30:33], v[168:171], v[204:207], v[30:33]
	v_mfma_f32_16x16x32_bf16 v[18:21], v[180:183], v[204:207], v[18:21]
	v_mfma_f32_16x16x32_bf16 v[14:17], v[168:171], v[214:217], v[14:17]
	v_mfma_f32_16x16x32_bf16 v[2:5], v[180:183], v[214:217], v[2:5]
	v_mfma_f32_16x16x32_bf16 v[62:65], v[172:175], v[192:195], v[62:65]
	v_mfma_f32_16x16x32_bf16 v[50:53], v[184:187], v[192:195], v[50:53]
	v_mfma_f32_16x16x32_bf16 v[46:49], v[172:175], v[200:203], v[46:49]
	v_mfma_f32_16x16x32_bf16 v[34:37], v[184:187], v[200:203], v[34:37]
	v_mfma_f32_16x16x32_bf16 v[30:33], v[172:175], v[210:213], v[30:33]
	v_mfma_f32_16x16x32_bf16 v[18:21], v[184:187], v[210:213], v[18:21]
	v_mfma_f32_16x16x32_bf16 v[14:17], v[172:175], v[218:221], v[14:17]
	v_mfma_f32_16x16x32_bf16 v[2:5], v[184:187], v[218:221], v[2:5]
	s_setprio 0
	s_barrier
	s_add_i32 s56, 0, 0x18000
	s_add_i32 s57, 0, 0x1c000
	v_add_u32_e32 v164, s56, v151
	v_add_u32_e32 v179, s57, v151
	ds_read_b128 v[146:149], v164
	ds_read_b128 v[156:159], v164 offset:1024
	ds_read_b128 v[160:163], v164 offset:2048
	ds_read_b128 v[164:167], v164 offset:3072
	ds_read_b128 v[168:171], v179
	ds_read_b128 v[172:175], v179 offset:1024
	ds_read_b128 v[180:183], v179 offset:2048
	ds_read_b128 v[184:187], v179 offset:3072
	s_add_u32 s28, s28, 0x40000
	s_addc_u32 s29, s29, 0
	s_mov_b32 m0, s39
	v_lshl_add_u64 v[226:227], s[28:29], 0, v[136:137]
	ds_read_b128 v[188:191], v155 offset:32768
	ds_read_b128 v[192:195], v155 offset:33792
	ds_read_b128 v[196:199], v155 offset:34816
	ds_read_b128 v[200:203], v155 offset:35840
	ds_read_b128 v[204:207], v155 offset:36864
	ds_read_b128 v[210:213], v155 offset:37888
	ds_read_b128 v[214:217], v155 offset:38912
	ds_read_b128 v[218:221], v155 offset:39936
	global_load_lds_dwordx4 v[226:227], off
	v_lshl_add_u64 v[226:227], s[28:29], 0, v[132:133]
	s_mov_b32 m0, s40
	s_nop 0
	global_load_lds_dwordx4 v[226:227], off
	s_waitcnt vmcnt(8)
	s_waitcnt lgkmcnt(0)
	s_barrier
	s_setprio 1
	s_waitcnt lgkmcnt(0)
	v_mfma_f32_16x16x32_bf16 v[122:125], v[146:149], v[188:191], v[122:125]
	v_mfma_f32_16x16x32_bf16 v[114:117], v[160:163], v[188:191], v[114:117]
	v_mfma_f32_16x16x32_bf16 v[106:109], v[146:149], v[196:199], v[106:109]
	v_mfma_f32_16x16x32_bf16 v[98:101], v[160:163], v[196:199], v[98:101]
	v_mfma_f32_16x16x32_bf16 v[90:93], v[146:149], v[204:207], v[90:93]
	v_mfma_f32_16x16x32_bf16 v[82:85], v[160:163], v[204:207], v[82:85]
	v_mfma_f32_16x16x32_bf16 v[74:77], v[146:149], v[214:217], v[74:77]
	v_mfma_f32_16x16x32_bf16 v[70:73], v[160:163], v[214:217], v[70:73]
	v_mfma_f32_16x16x32_bf16 v[122:125], v[156:159], v[192:195], v[122:125]
	v_mfma_f32_16x16x32_bf16 v[114:117], v[164:167], v[192:195], v[114:117]
	v_mfma_f32_16x16x32_bf16 v[106:109], v[156:159], v[200:203], v[106:109]
	v_mfma_f32_16x16x32_bf16 v[98:101], v[164:167], v[200:203], v[98:101]
	v_mfma_f32_16x16x32_bf16 v[90:93], v[156:159], v[210:213], v[90:93]
	v_mfma_f32_16x16x32_bf16 v[82:85], v[164:167], v[210:213], v[82:85]
	v_mfma_f32_16x16x32_bf16 v[74:77], v[156:159], v[218:221], v[74:77]
	v_mfma_f32_16x16x32_bf16 v[70:73], v[164:167], v[218:221], v[70:73]
	s_setprio 0
	s_setprio 1
	v_mfma_f32_16x16x32_bf16 v[126:129], v[168:171], v[188:191], v[126:129]
	v_mfma_f32_16x16x32_bf16 v[118:121], v[180:183], v[188:191], v[118:121]
	v_mfma_f32_16x16x32_bf16 v[110:113], v[168:171], v[196:199], v[110:113]
	v_mfma_f32_16x16x32_bf16 v[102:105], v[180:183], v[196:199], v[102:105]
	v_mfma_f32_16x16x32_bf16 v[94:97], v[168:171], v[204:207], v[94:97]
	v_mfma_f32_16x16x32_bf16 v[86:89], v[180:183], v[204:207], v[86:89]
	v_mfma_f32_16x16x32_bf16 v[78:81], v[168:171], v[214:217], v[78:81]
	v_mfma_f32_16x16x32_bf16 v[66:69], v[180:183], v[214:217], v[66:69]
	v_mfma_f32_16x16x32_bf16 v[126:129], v[172:175], v[192:195], v[126:129]
	v_mfma_f32_16x16x32_bf16 v[118:121], v[184:187], v[192:195], v[118:121]
	v_mfma_f32_16x16x32_bf16 v[110:113], v[172:175], v[200:203], v[110:113]
	v_mfma_f32_16x16x32_bf16 v[102:105], v[184:187], v[200:203], v[102:105]
	v_mfma_f32_16x16x32_bf16 v[94:97], v[172:175], v[210:213], v[94:97]
	v_mfma_f32_16x16x32_bf16 v[86:89], v[184:187], v[210:213], v[86:89]
	v_mfma_f32_16x16x32_bf16 v[78:81], v[172:175], v[218:221], v[78:81]
	v_mfma_f32_16x16x32_bf16 v[66:69], v[184:187], v[218:221], v[66:69]
	s_setprio 0
	s_barrier
	s_add_i32 s28, s56, s35
	v_lshl_add_u64 v[176:177], v[176:177], 0, s[10:11]
	s_mov_b32 m0, s28
	ds_read_b128 v[188:191], v155 offset:49152
	ds_read_b128 v[192:195], v155 offset:50176
	ds_read_b128 v[196:199], v155 offset:51200
	ds_read_b128 v[200:203], v155 offset:52224
	ds_read_b128 v[204:207], v155 offset:53248
	ds_read_b128 v[210:213], v155 offset:54272
	ds_read_b128 v[214:217], v155 offset:55296
	ds_read_b128 v[218:221], v155 offset:56320
	global_load_lds_dwordx4 v[176:177], off
	s_add_i32 m0, s28, 0x2000
	s_add_u32 s26, s26, 0x40080
	v_lshl_add_u64 v[176:177], v[208:209], 0, s[10:11]
	s_addc_u32 s27, s27, 0
	s_add_i32 s28, s57, s35
	global_load_lds_dwordx4 v[176:177], off
	v_lshl_add_u64 v[176:177], s[26:27], 0, v[134:135]
	s_mov_b32 m0, s28
	s_nop 0
	global_load_lds_dwordx4 v[176:177], off
	v_lshl_add_u64 v[176:177], s[26:27], 0, v[130:131]
	s_add_i32 m0, s28, 0x2000
	s_nop 0
	global_load_lds_dwordx4 v[176:177], off
	v_lshl_add_u64 v[176:177], v[222:223], 0, s[10:11]
	s_mov_b32 m0, s42
	s_nop 0
	global_load_lds_dwordx4 v[176:177], off
	v_lshl_add_u64 v[176:177], v[224:225], 0, s[10:11]
	s_mov_b32 m0, s43
	s_nop 0
	global_load_lds_dwordx4 v[176:177], off
	s_waitcnt vmcnt(8)
	s_waitcnt lgkmcnt(0)
	s_barrier
	s_setprio 1
	s_waitcnt lgkmcnt(0)
	v_mfma_f32_16x16x32_bf16 v[58:61], v[146:149], v[188:191], v[58:61]
	v_mfma_f32_16x16x32_bf16 v[54:57], v[160:163], v[188:191], v[54:57]
	v_mfma_f32_16x16x32_bf16 v[42:45], v[146:149], v[196:199], v[42:45]
	v_mfma_f32_16x16x32_bf16 v[38:41], v[160:163], v[196:199], v[38:41]
	v_mfma_f32_16x16x32_bf16 v[26:29], v[146:149], v[204:207], v[26:29]
	v_mfma_f32_16x16x32_bf16 v[22:25], v[160:163], v[204:207], v[22:25]
	v_mfma_f32_16x16x32_bf16 v[10:13], v[146:149], v[214:217], v[10:13]
	v_mfma_f32_16x16x32_bf16 v[6:9], v[160:163], v[214:217], v[6:9]
	v_mfma_f32_16x16x32_bf16 v[58:61], v[156:159], v[192:195], v[58:61]
	v_mfma_f32_16x16x32_bf16 v[54:57], v[164:167], v[192:195], v[54:57]
	v_mfma_f32_16x16x32_bf16 v[42:45], v[156:159], v[200:203], v[42:45]
	v_mfma_f32_16x16x32_bf16 v[38:41], v[164:167], v[200:203], v[38:41]
	v_mfma_f32_16x16x32_bf16 v[26:29], v[156:159], v[210:213], v[26:29]
	v_mfma_f32_16x16x32_bf16 v[22:25], v[164:167], v[210:213], v[22:25]
	v_mfma_f32_16x16x32_bf16 v[10:13], v[156:159], v[218:221], v[10:13]
	v_mfma_f32_16x16x32_bf16 v[6:9], v[164:167], v[218:221], v[6:9]
	s_setprio 0
	s_setprio 1
	v_mfma_f32_16x16x32_bf16 v[62:65], v[168:171], v[188:191], v[62:65]
	v_mfma_f32_16x16x32_bf16 v[50:53], v[180:183], v[188:191], v[50:53]
	v_mfma_f32_16x16x32_bf16 v[46:49], v[168:171], v[196:199], v[46:49]
	v_mfma_f32_16x16x32_bf16 v[34:37], v[180:183], v[196:199], v[34:37]
	v_mfma_f32_16x16x32_bf16 v[30:33], v[168:171], v[204:207], v[30:33]
	v_mfma_f32_16x16x32_bf16 v[18:21], v[180:183], v[204:207], v[18:21]
	v_mfma_f32_16x16x32_bf16 v[14:17], v[168:171], v[214:217], v[14:17]
	v_mfma_f32_16x16x32_bf16 v[2:5], v[180:183], v[214:217], v[2:5]
	v_mfma_f32_16x16x32_bf16 v[62:65], v[172:175], v[192:195], v[62:65]
	v_mfma_f32_16x16x32_bf16 v[50:53], v[184:187], v[192:195], v[50:53]
	v_mfma_f32_16x16x32_bf16 v[46:49], v[172:175], v[200:203], v[46:49]
	v_mfma_f32_16x16x32_bf16 v[34:37], v[184:187], v[200:203], v[34:37]
	v_mfma_f32_16x16x32_bf16 v[30:33], v[172:175], v[210:213], v[30:33]
	v_mfma_f32_16x16x32_bf16 v[18:21], v[184:187], v[210:213], v[18:21]
	v_mfma_f32_16x16x32_bf16 v[14:17], v[172:175], v[218:221], v[14:17]
	v_mfma_f32_16x16x32_bf16 v[2:5], v[184:187], v[218:221], v[2:5]
	s_setprio 0
	s_barrier
	s_add_i32 s55, s55, 2
	s_add_u32 s24, s24, 0x100
	s_addc_u32 s25, s25, 0
	s_add_u32 s53, s53, 0x100
	s_addc_u32 s54, s54, 0
	s_cmp_gt_u32 s55, 13
	s_cbranch_scc0 .LBB0_1558
	s_and_b64 vcc, exec, s[12:13]
	s_cbranch_vccz .LBB0_1561
	s_barrier
.LBB0_1561:
	v_lshl_add_u32 v146, s22, 8, v150
	v_ashrrev_i32_e32 v147, 31, v146
	v_lshl_add_u64 v[148:149], v[146:147], 2, s[8:9]
	global_load_dword v188, v[148:149], off
	global_load_dword v190, v[148:149], off offset:64
	global_load_dword v192, v[148:149], off offset:128
	global_load_dword v194, v[148:149], off offset:192
	global_load_dword v196, v[148:149], off offset:512
	global_load_dword v198, v[148:149], off offset:576
	global_load_dword v200, v[148:149], off offset:640
	global_load_dword v202, v[148:149], off offset:704
	s_andn2_b64 vcc, exec, s[2:3]
	s_mov_b64 s[2:3], -1
	v_lshl_or_b32 v158, s50, 7, v152
	v_mul_u32_u24_e32 v175, 0x1600, v146
	v_lshl_add_u32 v175, v158, 1, v175
	s_mov_b32 s26, s6
	s_mov_b32 s27, s7
	s_waitcnt vmcnt(7)
	v_mul_f32_e32 v172, 0xbfb8aa3b, v188
	v_mul_f32_e32 v173, v188, v188
	v_rcp_f32_e32 v174, v173
	v_mul_f32_e32 v156, v172, v122
	v_mul_f32_e32 v157, v172, v123
	v_mul_f32_e32 v158, v172, v124
	v_mul_f32_e32 v159, v172, v125
	v_mul_f32_e32 v160, v172, v114
	v_mul_f32_e32 v161, v172, v115
	v_mul_f32_e32 v162, v172, v116
	v_mul_f32_e32 v163, v172, v117
	v_exp_f32_e32 v156, v156
	v_exp_f32_e32 v157, v157
	v_exp_f32_e32 v158, v158
	v_exp_f32_e32 v159, v159
	v_exp_f32_e32 v160, v160
	v_exp_f32_e32 v161, v161
	v_exp_f32_e32 v162, v162
	v_exp_f32_e32 v163, v163
	v_mul_f32_e32 v126, v122, v126
	v_mul_f32_e32 v127, v123, v127
	v_mul_f32_e32 v128, v124, v128
	v_mul_f32_e32 v129, v125, v129
	v_mul_f32_e32 v118, v114, v118
	v_mul_f32_e32 v119, v115, v119
	v_mul_f32_e32 v120, v116, v120
	v_mul_f32_e32 v121, v117, v121
	v_fma_f32 v156, v156, v174, v174
	v_fma_f32 v157, v157, v174, v174
	v_fma_f32 v158, v158, v174, v174
	v_fma_f32 v159, v159, v174, v174
	v_fma_f32 v160, v160, v174, v174
	v_fma_f32 v161, v161, v174, v174
	v_fma_f32 v162, v162, v174, v174
	v_fma_f32 v163, v163, v174, v174
	v_rcp_f32_e32 v156, v156
	v_rcp_f32_e32 v157, v157
	v_rcp_f32_e32 v158, v158
	v_rcp_f32_e32 v159, v159
	v_rcp_f32_e32 v160, v160
	v_rcp_f32_e32 v161, v161
	v_rcp_f32_e32 v162, v162
	v_rcp_f32_e32 v163, v163
	s_nop 0
	v_mul_f32_e32 v126, v126, v156
	v_mul_f32_e32 v127, v127, v157
	v_mul_f32_e32 v128, v128, v158
	v_mul_f32_e32 v129, v129, v159
	v_mul_f32_e32 v118, v118, v160
	v_mul_f32_e32 v119, v119, v161
	v_mul_f32_e32 v120, v120, v162
	v_mul_f32_e32 v121, v121, v163
	v_cvt_pk_bf16_f32 v122, v126, v127
	v_cvt_pk_bf16_f32 v123, v128, v129
	v_cvt_pk_bf16_f32 v124, v118, v119
	v_cvt_pk_bf16_f32 v125, v120, v121
	global_store_dwordx4 v175, v[122:125], s[26:27]
	s_waitcnt vmcnt(7)
	v_mul_f32_e32 v172, 0xbfb8aa3b, v190
	v_mul_f32_e32 v173, v190, v190
	v_rcp_f32_e32 v174, v173
	v_mov_b32_e32 v114, 0
	v_mov_b32_e32 v115, 0
	v_mov_b32_e32 v116, 0
	v_mov_b32_e32 v117, 0
	v_mov_b32_e32 v118, 0
	v_mov_b32_e32 v119, 0
	v_mov_b32_e32 v120, 0
	v_mov_b32_e32 v121, 0
	v_mov_b32_e32 v122, 0
	v_mov_b32_e32 v123, 0
	v_mov_b32_e32 v124, 0
	v_mov_b32_e32 v125, 0
	v_mov_b32_e32 v126, 0
	v_mov_b32_e32 v127, 0
	v_mov_b32_e32 v128, 0
	v_mov_b32_e32 v129, 0
	v_mul_f32_e32 v164, v172, v106
	v_mul_f32_e32 v165, v172, v107
	v_mul_f32_e32 v166, v172, v108
	v_mul_f32_e32 v167, v172, v109
	v_mul_f32_e32 v168, v172, v98
	v_mul_f32_e32 v169, v172, v99
	v_mul_f32_e32 v170, v172, v100
	v_mul_f32_e32 v171, v172, v101
	v_exp_f32_e32 v164, v164
	v_exp_f32_e32 v165, v165
	v_exp_f32_e32 v166, v166
	v_exp_f32_e32 v167, v167
	v_exp_f32_e32 v168, v168
	v_exp_f32_e32 v169, v169
	v_exp_f32_e32 v170, v170
	v_exp_f32_e32 v171, v171
	v_mul_f32_e32 v110, v106, v110
	v_mul_f32_e32 v111, v107, v111
	v_mul_f32_e32 v112, v108, v112
	v_mul_f32_e32 v113, v109, v113
	v_mul_f32_e32 v102, v98, v102
	v_mul_f32_e32 v103, v99, v103
	v_mul_f32_e32 v104, v100, v104
	v_mul_f32_e32 v105, v101, v105
	v_fma_f32 v164, v164, v174, v174
	v_fma_f32 v165, v165, v174, v174
	v_fma_f32 v166, v166, v174, v174
	v_fma_f32 v167, v167, v174, v174
	v_fma_f32 v168, v168, v174, v174
	v_fma_f32 v169, v169, v174, v174
	v_fma_f32 v170, v170, v174, v174
	v_fma_f32 v171, v171, v174, v174
	v_rcp_f32_e32 v164, v164
	v_rcp_f32_e32 v165, v165
	v_rcp_f32_e32 v166, v166
	v_rcp_f32_e32 v167, v167
	v_rcp_f32_e32 v168, v168
	v_rcp_f32_e32 v169, v169
	v_rcp_f32_e32 v170, v170
	v_rcp_f32_e32 v171, v171
	s_add_u32 s26, s26, 0x16000
	s_addc_u32 s27, s27, 0
	v_mul_f32_e32 v110, v110, v164
	v_mul_f32_e32 v111, v111, v165
	v_mul_f32_e32 v112, v112, v166
	v_mul_f32_e32 v113, v113, v167
	v_mul_f32_e32 v102, v102, v168
	v_mul_f32_e32 v103, v103, v169
	v_mul_f32_e32 v104, v104, v170
	v_mul_f32_e32 v105, v105, v171
	v_cvt_pk_bf16_f32 v106, v110, v111
	v_cvt_pk_bf16_f32 v107, v112, v113
	v_cvt_pk_bf16_f32 v108, v102, v103
	v_cvt_pk_bf16_f32 v109, v104, v105
	global_store_dwordx4 v175, v[106:109], s[26:27]
	s_waitcnt vmcnt(7)
	v_mul_f32_e32 v172, 0xbfb8aa3b, v192
	v_mul_f32_e32 v173, v192, v192
	v_rcp_f32_e32 v174, v173
	v_mov_b32_e32 v98, 0
	v_mov_b32_e32 v99, 0
	v_mov_b32_e32 v100, 0
	v_mov_b32_e32 v101, 0
	v_mov_b32_e32 v102, 0
	v_mov_b32_e32 v103, 0
	v_mov_b32_e32 v104, 0
	v_mov_b32_e32 v105, 0
	v_mov_b32_e32 v106, 0
	v_mov_b32_e32 v107, 0
	v_mov_b32_e32 v108, 0
	v_mov_b32_e32 v109, 0
	v_mov_b32_e32 v110, 0
	v_mov_b32_e32 v111, 0
	v_mov_b32_e32 v112, 0
	v_mov_b32_e32 v113, 0
	v_mul_f32_e32 v156, v172, v90
	v_mul_f32_e32 v157, v172, v91
	v_mul_f32_e32 v158, v172, v92
	v_mul_f32_e32 v159, v172, v93
	v_mul_f32_e32 v160, v172, v82
	v_mul_f32_e32 v161, v172, v83
	v_mul_f32_e32 v162, v172, v84
	v_mul_f32_e32 v163, v172, v85
	v_exp_f32_e32 v156, v156
	v_exp_f32_e32 v157, v157
	v_exp_f32_e32 v158, v158
	v_exp_f32_e32 v159, v159
	v_exp_f32_e32 v160, v160
	v_exp_f32_e32 v161, v161
	v_exp_f32_e32 v162, v162
	v_exp_f32_e32 v163, v163
	v_mul_f32_e32 v94, v90, v94
	v_mul_f32_e32 v95, v91, v95
	v_mul_f32_e32 v96, v92, v96
	v_mul_f32_e32 v97, v93, v97
	v_mul_f32_e32 v86, v82, v86
	v_mul_f32_e32 v87, v83, v87
	v_mul_f32_e32 v88, v84, v88
	v_mul_f32_e32 v89, v85, v89
	v_fma_f32 v156, v156, v174, v174
	v_fma_f32 v157, v157, v174, v174
	v_fma_f32 v158, v158, v174, v174
	v_fma_f32 v159, v159, v174, v174
	v_fma_f32 v160, v160, v174, v174
	v_fma_f32 v161, v161, v174, v174
	v_fma_f32 v162, v162, v174, v174
	v_fma_f32 v163, v163, v174, v174
	v_rcp_f32_e32 v156, v156
	v_rcp_f32_e32 v157, v157
	v_rcp_f32_e32 v158, v158
	v_rcp_f32_e32 v159, v159
	v_rcp_f32_e32 v160, v160
	v_rcp_f32_e32 v161, v161
	v_rcp_f32_e32 v162, v162
	v_rcp_f32_e32 v163, v163
	s_add_u32 s26, s26, 0x16000
	s_addc_u32 s27, s27, 0
	v_mul_f32_e32 v94, v94, v156
	v_mul_f32_e32 v95, v95, v157
	v_mul_f32_e32 v96, v96, v158
	v_mul_f32_e32 v97, v97, v159
	v_mul_f32_e32 v86, v86, v160
	v_mul_f32_e32 v87, v87, v161
	v_mul_f32_e32 v88, v88, v162
	v_mul_f32_e32 v89, v89, v163
	v_cvt_pk_bf16_f32 v90, v94, v95
	v_cvt_pk_bf16_f32 v91, v96, v97
	v_cvt_pk_bf16_f32 v92, v86, v87
	v_cvt_pk_bf16_f32 v93, v88, v89
	global_store_dwordx4 v175, v[90:93], s[26:27]
	s_waitcnt vmcnt(7)
	v_mul_f32_e32 v172, 0xbfb8aa3b, v194
	v_mul_f32_e32 v173, v194, v194
	v_rcp_f32_e32 v174, v173
	v_mov_b32_e32 v82, 0
	v_mov_b32_e32 v83, 0
	v_mov_b32_e32 v84, 0
	v_mov_b32_e32 v85, 0
	v_mov_b32_e32 v86, 0
	v_mov_b32_e32 v87, 0
	v_mov_b32_e32 v88, 0
	v_mov_b32_e32 v89, 0
	v_mov_b32_e32 v90, 0
	v_mov_b32_e32 v91, 0
	v_mov_b32_e32 v92, 0
	v_mov_b32_e32 v93, 0
	v_mov_b32_e32 v94, 0
	v_mov_b32_e32 v95, 0
	v_mov_b32_e32 v96, 0
	v_mov_b32_e32 v97, 0
	v_mul_f32_e32 v164, v172, v74
	v_mul_f32_e32 v165, v172, v75
	v_mul_f32_e32 v166, v172, v76
	v_mul_f32_e32 v167, v172, v77
	v_mul_f32_e32 v168, v172, v70
	v_mul_f32_e32 v169, v172, v71
	v_mul_f32_e32 v170, v172, v72
	v_mul_f32_e32 v171, v172, v73
	v_exp_f32_e32 v164, v164
	v_exp_f32_e32 v165, v165
	v_exp_f32_e32 v166, v166
	v_exp_f32_e32 v167, v167
	v_exp_f32_e32 v168, v168
	v_exp_f32_e32 v169, v169
	v_exp_f32_e32 v170, v170
	v_exp_f32_e32 v171, v171
	v_mul_f32_e32 v78, v74, v78
	v_mul_f32_e32 v79, v75, v79
	v_mul_f32_e32 v80, v76, v80
	v_mul_f32_e32 v81, v77, v81
	v_mul_f32_e32 v66, v70, v66
	v_mul_f32_e32 v67, v71, v67
	v_mul_f32_e32 v68, v72, v68
	v_mul_f32_e32 v69, v73, v69
	v_fma_f32 v164, v164, v174, v174
	v_fma_f32 v165, v165, v174, v174
	v_fma_f32 v166, v166, v174, v174
	v_fma_f32 v167, v167, v174, v174
	v_fma_f32 v168, v168, v174, v174
	v_fma_f32 v169, v169, v174, v174
	v_fma_f32 v170, v170, v174, v174
	v_fma_f32 v171, v171, v174, v174
	v_rcp_f32_e32 v164, v164
	v_rcp_f32_e32 v165, v165
	v_rcp_f32_e32 v166, v166
	v_rcp_f32_e32 v167, v167
	v_rcp_f32_e32 v168, v168
	v_rcp_f32_e32 v169, v169
	v_rcp_f32_e32 v170, v170
	v_rcp_f32_e32 v171, v171
	s_add_u32 s26, s26, 0x16000
	s_addc_u32 s27, s27, 0
	v_mul_f32_e32 v78, v78, v164
	v_mul_f32_e32 v79, v79, v165
	v_mul_f32_e32 v80, v80, v166
	v_mul_f32_e32 v81, v81, v167
	v_mul_f32_e32 v66, v66, v168
	v_mul_f32_e32 v67, v67, v169
	v_mul_f32_e32 v68, v68, v170
	v_mul_f32_e32 v69, v69, v171
	v_cvt_pk_bf16_f32 v74, v78, v79
	v_cvt_pk_bf16_f32 v75, v80, v81
	v_cvt_pk_bf16_f32 v76, v66, v67
	v_cvt_pk_bf16_f32 v77, v68, v69
	global_store_dwordx4 v175, v[74:77], s[26:27]
	s_waitcnt vmcnt(7)
	v_mul_f32_e32 v172, 0xbfb8aa3b, v196
	v_mul_f32_e32 v173, v196, v196
	v_rcp_f32_e32 v174, v173
	v_mov_b32_e32 v66, 0
	v_mov_b32_e32 v67, 0
	v_mov_b32_e32 v68, 0
	v_mov_b32_e32 v69, 0
	v_mov_b32_e32 v70, 0
	v_mov_b32_e32 v71, 0
	v_mov_b32_e32 v72, 0
	v_mov_b32_e32 v73, 0
	v_mov_b32_e32 v74, 0
	v_mov_b32_e32 v75, 0
	v_mov_b32_e32 v76, 0
	v_mov_b32_e32 v77, 0
	v_mov_b32_e32 v78, 0
	v_mov_b32_e32 v79, 0
	v_mov_b32_e32 v80, 0
	v_mov_b32_e32 v81, 0
	v_mul_f32_e32 v156, v172, v58
	v_mul_f32_e32 v157, v172, v59
	v_mul_f32_e32 v158, v172, v60
	v_mul_f32_e32 v159, v172, v61
	v_mul_f32_e32 v160, v172, v54
	v_mul_f32_e32 v161, v172, v55
	v_mul_f32_e32 v162, v172, v56
	v_mul_f32_e32 v163, v172, v57
	v_exp_f32_e32 v156, v156
	v_exp_f32_e32 v157, v157
	v_exp_f32_e32 v158, v158
	v_exp_f32_e32 v159, v159
	v_exp_f32_e32 v160, v160
	v_exp_f32_e32 v161, v161
	v_exp_f32_e32 v162, v162
	v_exp_f32_e32 v163, v163
	v_mul_f32_e32 v62, v58, v62
	v_mul_f32_e32 v63, v59, v63
	v_mul_f32_e32 v64, v60, v64
	v_mul_f32_e32 v65, v61, v65
	v_mul_f32_e32 v50, v54, v50
	v_mul_f32_e32 v51, v55, v51
	v_mul_f32_e32 v52, v56, v52
	v_mul_f32_e32 v53, v57, v53
	v_fma_f32 v156, v156, v174, v174
	v_fma_f32 v157, v157, v174, v174
	v_fma_f32 v158, v158, v174, v174
	v_fma_f32 v159, v159, v174, v174
	v_fma_f32 v160, v160, v174, v174
	v_fma_f32 v161, v161, v174, v174
	v_fma_f32 v162, v162, v174, v174
	v_fma_f32 v163, v163, v174, v174
	v_rcp_f32_e32 v156, v156
	v_rcp_f32_e32 v157, v157
	v_rcp_f32_e32 v158, v158
	v_rcp_f32_e32 v159, v159
	v_rcp_f32_e32 v160, v160
	v_rcp_f32_e32 v161, v161
	v_rcp_f32_e32 v162, v162
	v_rcp_f32_e32 v163, v163
	s_add_u32 s26, s26, 0x6e000
	s_addc_u32 s27, s27, 0
	v_mul_f32_e32 v62, v62, v156
	v_mul_f32_e32 v63, v63, v157
	v_mul_f32_e32 v64, v64, v158
	v_mul_f32_e32 v65, v65, v159
	v_mul_f32_e32 v50, v50, v160
	v_mul_f32_e32 v51, v51, v161
	v_mul_f32_e32 v52, v52, v162
	v_mul_f32_e32 v53, v53, v163
	v_cvt_pk_bf16_f32 v58, v62, v63
	v_cvt_pk_bf16_f32 v59, v64, v65
	v_cvt_pk_bf16_f32 v60, v50, v51
	v_cvt_pk_bf16_f32 v61, v52, v53
	global_store_dwordx4 v175, v[58:61], s[26:27]
	s_waitcnt vmcnt(7)
	v_mul_f32_e32 v172, 0xbfb8aa3b, v198
	v_mul_f32_e32 v173, v198, v198
	v_rcp_f32_e32 v174, v173
	v_mov_b32_e32 v50, 0
	v_mov_b32_e32 v51, 0
	v_mov_b32_e32 v52, 0
	v_mov_b32_e32 v53, 0
	v_mov_b32_e32 v54, 0
	v_mov_b32_e32 v55, 0
	v_mov_b32_e32 v56, 0
	v_mov_b32_e32 v57, 0
	v_mov_b32_e32 v58, 0
	v_mov_b32_e32 v59, 0
	v_mov_b32_e32 v60, 0
	v_mov_b32_e32 v61, 0
	v_mov_b32_e32 v62, 0
	v_mov_b32_e32 v63, 0
	v_mov_b32_e32 v64, 0
	v_mov_b32_e32 v65, 0
	v_mul_f32_e32 v164, v172, v42
	v_mul_f32_e32 v165, v172, v43
	v_mul_f32_e32 v166, v172, v44
	v_mul_f32_e32 v167, v172, v45
	v_mul_f32_e32 v168, v172, v38
	v_mul_f32_e32 v169, v172, v39
	v_mul_f32_e32 v170, v172, v40
	v_mul_f32_e32 v171, v172, v41
	v_exp_f32_e32 v164, v164
	v_exp_f32_e32 v165, v165
	v_exp_f32_e32 v166, v166
	v_exp_f32_e32 v167, v167
	v_exp_f32_e32 v168, v168
	v_exp_f32_e32 v169, v169
	v_exp_f32_e32 v170, v170
	v_exp_f32_e32 v171, v171
	v_mul_f32_e32 v46, v42, v46
	v_mul_f32_e32 v47, v43, v47
	v_mul_f32_e32 v48, v44, v48
	v_mul_f32_e32 v49, v45, v49
	v_mul_f32_e32 v34, v38, v34
	v_mul_f32_e32 v35, v39, v35
	v_mul_f32_e32 v36, v40, v36
	v_mul_f32_e32 v37, v41, v37
	v_fma_f32 v164, v164, v174, v174
	v_fma_f32 v165, v165, v174, v174
	v_fma_f32 v166, v166, v174, v174
	v_fma_f32 v167, v167, v174, v174
	v_fma_f32 v168, v168, v174, v174
	v_fma_f32 v169, v169, v174, v174
	v_fma_f32 v170, v170, v174, v174
	v_fma_f32 v171, v171, v174, v174
	v_rcp_f32_e32 v164, v164
	v_rcp_f32_e32 v165, v165
	v_rcp_f32_e32 v166, v166
	v_rcp_f32_e32 v167, v167
	v_rcp_f32_e32 v168, v168
	v_rcp_f32_e32 v169, v169
	v_rcp_f32_e32 v170, v170
	v_rcp_f32_e32 v171, v171
	s_add_u32 s26, s26, 0x16000
	s_addc_u32 s27, s27, 0
	v_mul_f32_e32 v46, v46, v164
	v_mul_f32_e32 v47, v47, v165
	v_mul_f32_e32 v48, v48, v166
	v_mul_f32_e32 v49, v49, v167
	v_mul_f32_e32 v34, v34, v168
	v_mul_f32_e32 v35, v35, v169
	v_mul_f32_e32 v36, v36, v170
	v_mul_f32_e32 v37, v37, v171
	v_cvt_pk_bf16_f32 v42, v46, v47
	v_cvt_pk_bf16_f32 v43, v48, v49
	v_cvt_pk_bf16_f32 v44, v34, v35
	v_cvt_pk_bf16_f32 v45, v36, v37
	global_store_dwordx4 v175, v[42:45], s[26:27]
	s_waitcnt vmcnt(7)
	v_mul_f32_e32 v172, 0xbfb8aa3b, v200
	v_mul_f32_e32 v173, v200, v200
	v_rcp_f32_e32 v174, v173
	v_mov_b32_e32 v34, 0
	v_mov_b32_e32 v35, 0
	v_mov_b32_e32 v36, 0
	v_mov_b32_e32 v37, 0
	v_mov_b32_e32 v38, 0
	v_mov_b32_e32 v39, 0
	v_mov_b32_e32 v40, 0
	v_mov_b32_e32 v41, 0
	v_mov_b32_e32 v42, 0
	v_mov_b32_e32 v43, 0
	v_mov_b32_e32 v44, 0
	v_mov_b32_e32 v45, 0
	v_mov_b32_e32 v46, 0
	v_mov_b32_e32 v47, 0
	v_mov_b32_e32 v48, 0
	v_mov_b32_e32 v49, 0
	v_mul_f32_e32 v156, v172, v26
	v_mul_f32_e32 v157, v172, v27
	v_mul_f32_e32 v158, v172, v28
	v_mul_f32_e32 v159, v172, v29
	v_mul_f32_e32 v160, v172, v22
	v_mul_f32_e32 v161, v172, v23
	v_mul_f32_e32 v162, v172, v24
	v_mul_f32_e32 v163, v172, v25
	v_exp_f32_e32 v156, v156
	v_exp_f32_e32 v157, v157
	v_exp_f32_e32 v158, v158
	v_exp_f32_e32 v159, v159
	v_exp_f32_e32 v160, v160
	v_exp_f32_e32 v161, v161
	v_exp_f32_e32 v162, v162
	v_exp_f32_e32 v163, v163
	v_mul_f32_e32 v30, v26, v30
	v_mul_f32_e32 v31, v27, v31
	v_mul_f32_e32 v32, v28, v32
	v_mul_f32_e32 v33, v29, v33
	v_mul_f32_e32 v18, v22, v18
	v_mul_f32_e32 v19, v23, v19
	v_mul_f32_e32 v20, v24, v20
	v_mul_f32_e32 v21, v25, v21
	v_fma_f32 v156, v156, v174, v174
	v_fma_f32 v157, v157, v174, v174
	v_fma_f32 v158, v158, v174, v174
	v_fma_f32 v159, v159, v174, v174
	v_fma_f32 v160, v160, v174, v174
	v_fma_f32 v161, v161, v174, v174
	v_fma_f32 v162, v162, v174, v174
	v_fma_f32 v163, v163, v174, v174
	v_rcp_f32_e32 v156, v156
	v_rcp_f32_e32 v157, v157
	v_rcp_f32_e32 v158, v158
	v_rcp_f32_e32 v159, v159
	v_rcp_f32_e32 v160, v160
	v_rcp_f32_e32 v161, v161
	v_rcp_f32_e32 v162, v162
	v_rcp_f32_e32 v163, v163
	s_add_u32 s26, s26, 0x16000
	s_addc_u32 s27, s27, 0
	v_mul_f32_e32 v30, v30, v156
	v_mul_f32_e32 v31, v31, v157
	v_mul_f32_e32 v32, v32, v158
	v_mul_f32_e32 v33, v33, v159
	v_mul_f32_e32 v18, v18, v160
	v_mul_f32_e32 v19, v19, v161
	v_mul_f32_e32 v20, v20, v162
	v_mul_f32_e32 v21, v21, v163
	v_cvt_pk_bf16_f32 v26, v30, v31
	v_cvt_pk_bf16_f32 v27, v32, v33
	v_cvt_pk_bf16_f32 v28, v18, v19
	v_cvt_pk_bf16_f32 v29, v20, v21
	global_store_dwordx4 v175, v[26:29], s[26:27]
	s_waitcnt vmcnt(7)
	v_mul_f32_e32 v172, 0xbfb8aa3b, v202
	v_mul_f32_e32 v173, v202, v202
	v_rcp_f32_e32 v174, v173
	v_mov_b32_e32 v18, 0
	v_mov_b32_e32 v19, 0
	v_mov_b32_e32 v20, 0
	v_mov_b32_e32 v21, 0
	v_mov_b32_e32 v22, 0
	v_mov_b32_e32 v23, 0
	v_mov_b32_e32 v24, 0
	v_mov_b32_e32 v25, 0
	v_mov_b32_e32 v26, 0
	v_mov_b32_e32 v27, 0
	v_mov_b32_e32 v28, 0
	v_mov_b32_e32 v29, 0
	v_mov_b32_e32 v30, 0
	v_mov_b32_e32 v31, 0
	v_mov_b32_e32 v32, 0
	v_mov_b32_e32 v33, 0
	v_mul_f32_e32 v164, v172, v10
	v_mul_f32_e32 v165, v172, v11
	v_mul_f32_e32 v166, v172, v12
	v_mul_f32_e32 v167, v172, v13
	v_mul_f32_e32 v168, v172, v6
	v_mul_f32_e32 v169, v172, v7
	v_mul_f32_e32 v170, v172, v8
	v_mul_f32_e32 v171, v172, v9
	v_exp_f32_e32 v164, v164
	v_exp_f32_e32 v165, v165
	v_exp_f32_e32 v166, v166
	v_exp_f32_e32 v167, v167
	v_exp_f32_e32 v168, v168
	v_exp_f32_e32 v169, v169
	v_exp_f32_e32 v170, v170
	v_exp_f32_e32 v171, v171
	v_mul_f32_e32 v14, v10, v14
	v_mul_f32_e32 v15, v11, v15
	v_mul_f32_e32 v16, v12, v16
	v_mul_f32_e32 v17, v13, v17
	v_mul_f32_e32 v2, v6, v2
	v_mul_f32_e32 v3, v7, v3
	v_mul_f32_e32 v4, v8, v4
	v_mul_f32_e32 v5, v9, v5
	v_fma_f32 v164, v164, v174, v174
	v_fma_f32 v165, v165, v174, v174
	v_fma_f32 v166, v166, v174, v174
	v_fma_f32 v167, v167, v174, v174
	v_fma_f32 v168, v168, v174, v174
	v_fma_f32 v169, v169, v174, v174
	v_fma_f32 v170, v170, v174, v174
	v_fma_f32 v171, v171, v174, v174
	v_rcp_f32_e32 v164, v164
	v_rcp_f32_e32 v165, v165
	v_rcp_f32_e32 v166, v166
	v_rcp_f32_e32 v167, v167
	v_rcp_f32_e32 v168, v168
	v_rcp_f32_e32 v169, v169
	v_rcp_f32_e32 v170, v170
	v_rcp_f32_e32 v171, v171
	s_add_u32 s26, s26, 0x16000
	s_addc_u32 s27, s27, 0
	v_mul_f32_e32 v14, v14, v164
	v_mul_f32_e32 v15, v15, v165
	v_mul_f32_e32 v16, v16, v166
	v_mul_f32_e32 v17, v17, v167
	v_mul_f32_e32 v2, v2, v168
	v_mul_f32_e32 v3, v3, v169
	v_mul_f32_e32 v4, v4, v170
	v_mul_f32_e32 v5, v5, v171
	v_cvt_pk_bf16_f32 v10, v14, v15
	v_cvt_pk_bf16_f32 v11, v16, v17
	v_cvt_pk_bf16_f32 v12, v2, v3
	v_cvt_pk_bf16_f32 v13, v4, v5
	global_store_dwordx4 v175, v[10:13], s[26:27]
	s_nop 1
	v_mov_b32_e32 v2, 0
	v_mov_b32_e32 v3, 0
	v_mov_b32_e32 v4, 0
	v_mov_b32_e32 v5, 0
	v_mov_b32_e32 v6, 0
	v_mov_b32_e32 v7, 0
	v_mov_b32_e32 v8, 0
	v_mov_b32_e32 v9, 0
	v_mov_b32_e32 v10, 0
	v_mov_b32_e32 v11, 0
	v_mov_b32_e32 v12, 0
	v_mov_b32_e32 v13, 0
	v_mov_b32_e32 v14, 0
	v_mov_b32_e32 v15, 0
	v_mov_b32_e32 v16, 0
	v_mov_b32_e32 v17, 0
	s_mov_b32 s59, 1
	s_cbranch_vccnz .LBB0_1554
	s_andn2_b64 vcc, exec, s[4:5]
	s_cbranch_vccnz .LBB0_1553
	s_barrier
	s_branch .LBB0_1553
